# PROJ fast epilogue extended to gelu tiles (packed gelu, same per-element operation order)
# baseline (speedup 1.0000x reference)
.LBB0_812:
	s_cmp_eq_u32 s26, s43
	s_cbranch_scc1 .Lpj_slow
	v_lshl_add_u32 v176, s6, 8, v223
	v_or_b32_e32 v177, 16, v176
	v_or_b32_e32 v178, 32, v176
	v_or_b32_e32 v179, 48, v176
	v_add_u32_e32 v180, 0x80, v176
	v_add_u32_e32 v181, 0x90, v176
	v_add_u32_e32 v182, 0xa0, v176
	v_add_u32_e32 v183, 0xb0, v176
	v_lshl_or_b32 v214, s26, 8, v225
	v_ashrrev_i32_e32 v215, 31, v214
	v_lshlrev_b64 v[214:215], 1, v[214:215]
	v_lshl_add_u64 v[214:215], s[14:15], 0, v[214:215]
	s_cmp_eq_u32 s101, s6
	s_cbranch_scc1 .Lpj_rs_cached
	v_mov_b32_e32 v152, v176
	v_ashrrev_i32_e32 v153, 31, v176
	v_lshlrev_b64 v[152:153], 6, v[152:153]
	v_lshl_add_u64 v[152:153], v[170:171], 0, v[152:153]
	global_load_dwordx4 v[184:187], v[152:153], off
	v_mov_b32_e32 v152, v177
	v_ashrrev_i32_e32 v153, 31, v177
	v_lshlrev_b64 v[152:153], 6, v[152:153]
	v_lshl_add_u64 v[152:153], v[170:171], 0, v[152:153]
	global_load_dwordx4 v[188:191], v[152:153], off
	v_mov_b32_e32 v152, v178
	v_ashrrev_i32_e32 v153, 31, v178
	v_lshlrev_b64 v[152:153], 6, v[152:153]
	v_lshl_add_u64 v[152:153], v[170:171], 0, v[152:153]
	global_load_dwordx4 v[192:195], v[152:153], off
	v_mov_b32_e32 v152, v179
	v_ashrrev_i32_e32 v153, 31, v179
	v_lshlrev_b64 v[152:153], 6, v[152:153]
	v_lshl_add_u64 v[152:153], v[170:171], 0, v[152:153]
	global_load_dwordx4 v[196:199], v[152:153], off
	v_mov_b32_e32 v152, v180
	v_ashrrev_i32_e32 v153, 31, v180
	v_lshlrev_b64 v[152:153], 6, v[152:153]
	v_lshl_add_u64 v[152:153], v[170:171], 0, v[152:153]
	global_load_dwordx4 v[200:203], v[152:153], off
	v_mov_b32_e32 v152, v181
	v_ashrrev_i32_e32 v153, 31, v181
	v_lshlrev_b64 v[152:153], 6, v[152:153]
	v_lshl_add_u64 v[152:153], v[170:171], 0, v[152:153]
	global_load_dwordx4 v[204:207], v[152:153], off
	v_mov_b32_e32 v152, v182
	v_ashrrev_i32_e32 v153, 31, v182
	v_lshlrev_b64 v[152:153], 6, v[152:153]
	v_lshl_add_u64 v[152:153], v[170:171], 0, v[152:153]
	global_load_dwordx4 v[228:231], v[152:153], off
	v_mov_b32_e32 v152, v183
	v_ashrrev_i32_e32 v153, 31, v183
	v_lshlrev_b64 v[152:153], 6, v[152:153]
	v_lshl_add_u64 v[152:153], v[170:171], 0, v[152:153]
	global_load_dwordx4 v[232:235], v[152:153], off
	v_xor_b32_e32 v146, 16, v211
	v_lshlrev_b32_e32 v146, 2, v146
	v_xor_b32_e32 v147, 32, v211
	v_lshlrev_b32_e32 v147, 2, v147
	s_waitcnt vmcnt(0)
	v_add_f32_e32 v152, v184, v185
	v_add_f32_e32 v153, v186, v187
	v_add_f32_e32 v130, v152, v153
	v_add_f32_e32 v152, v188, v189
	v_add_f32_e32 v153, v190, v191
	v_add_f32_e32 v132, v152, v153
	v_add_f32_e32 v152, v192, v193
	v_add_f32_e32 v153, v194, v195
	v_add_f32_e32 v134, v152, v153
	v_add_f32_e32 v152, v196, v197
	v_add_f32_e32 v153, v198, v199
	v_add_f32_e32 v136, v152, v153
	v_add_f32_e32 v152, v200, v201
	v_add_f32_e32 v153, v202, v203
	v_add_f32_e32 v138, v152, v153
	v_add_f32_e32 v152, v204, v205
	v_add_f32_e32 v153, v206, v207
	v_add_f32_e32 v140, v152, v153
	v_add_f32_e32 v152, v228, v229
	v_add_f32_e32 v153, v230, v231
	v_add_f32_e32 v142, v152, v153
	v_add_f32_e32 v152, v232, v233
	v_add_f32_e32 v153, v234, v235
	v_add_f32_e32 v144, v152, v153
	ds_bpermute_b32 v184, v146, v130
	ds_bpermute_b32 v188, v146, v132
	ds_bpermute_b32 v192, v146, v134
	ds_bpermute_b32 v196, v146, v136
	ds_bpermute_b32 v200, v146, v138
	ds_bpermute_b32 v204, v146, v140
	ds_bpermute_b32 v228, v146, v142
	ds_bpermute_b32 v232, v146, v144
	s_waitcnt lgkmcnt(0)
	v_add_f32_e32 v130, v130, v184
	v_add_f32_e32 v132, v132, v188
	v_add_f32_e32 v134, v134, v192
	v_add_f32_e32 v136, v136, v196
	v_add_f32_e32 v138, v138, v200
	v_add_f32_e32 v140, v140, v204
	v_add_f32_e32 v142, v142, v228
	v_add_f32_e32 v144, v144, v232
	ds_bpermute_b32 v184, v147, v130
	ds_bpermute_b32 v188, v147, v132
	ds_bpermute_b32 v192, v147, v134
	ds_bpermute_b32 v196, v147, v136
	ds_bpermute_b32 v200, v147, v138
	ds_bpermute_b32 v204, v147, v140
	ds_bpermute_b32 v228, v147, v142
	ds_bpermute_b32 v232, v147, v144
	s_waitcnt lgkmcnt(0)
	v_add_f32_e32 v130, v130, v184
	v_add_f32_e32 v132, v132, v188
	v_add_f32_e32 v134, v134, v192
	v_add_f32_e32 v136, v136, v196
	v_add_f32_e32 v138, v138, v200
	v_add_f32_e32 v140, v140, v204
	v_add_f32_e32 v142, v142, v228
	v_add_f32_e32 v144, v144, v232
	s_mov_b32 s100, 0x3a800000
	v_fma_f32 v130, v130, s100, v240
	v_fma_f32 v132, v132, s100, v240
	v_fma_f32 v134, v134, s100, v240
	v_fma_f32 v136, v136, s100, v240
	v_fma_f32 v138, v138, s100, v240
	v_fma_f32 v140, v140, s100, v240
	v_fma_f32 v142, v142, s100, v240
	v_fma_f32 v144, v144, s100, v240
	v_rsq_f32_e32 v130, v130
	v_rsq_f32_e32 v132, v132
	v_rsq_f32_e32 v134, v134
	v_rsq_f32_e32 v136, v136
	v_rsq_f32_e32 v138, v138
	v_rsq_f32_e32 v140, v140
	v_rsq_f32_e32 v142, v142
	v_rsq_f32_e32 v144, v144
	s_nop 0
	v_mov_b32_e32 v250, v130
	v_mov_b32_e32 v168, v132
	v_mov_b32_e32 v169, v134
	v_mov_b32_e32 v227, v136
	v_mov_b32_e32 v238, v138
	v_mov_b32_e32 v239, v140
	v_mov_b32_e32 v248, v142
	v_mov_b32_e32 v249, v144
	s_mov_b32 s101, s6
	s_branch .Lpj_rs_done

.Lpj_rs_done:
	s_lshl_b32 s100, 1, s26
	s_and_b32 s100, s100, s42
	s_cmp_lg_u32 s100, 0
	s_cbranch_scc1 .Lpj_gelu
	v_mad_i64_i32 v[208:209], vcc, s41, v176, 0
	v_lshl_add_u64 v[208:209], v[208:209], 1, v[214:215]
	v_pk_mul_f32 v[126:127], v[126:127], v[130:131] op_sel_hi:[1,0]
	v_pk_mul_f32 v[128:129], v[128:129], v[130:131] op_sel_hi:[1,0]
	v_pk_mul_f32 v[122:123], v[122:123], v[130:131] op_sel_hi:[1,0]
	v_pk_mul_f32 v[124:125], v[124:125], v[130:131] op_sel_hi:[1,0]
	v_cvt_pk_bf16_f32 v162, v126, v127
	v_cvt_pk_bf16_f32 v163, v128, v129
	v_cvt_pk_bf16_f32 v164, v122, v123
	v_cvt_pk_bf16_f32 v165, v124, v125
	global_store_dwordx4 v[208:209], v[162:165], off
	v_pk_mul_f32 v[118:119], v[118:119], v[130:131] op_sel_hi:[1,0]
	v_pk_mul_f32 v[120:121], v[120:121], v[130:131] op_sel_hi:[1,0]
	v_pk_mul_f32 v[114:115], v[114:115], v[130:131] op_sel_hi:[1,0]
	v_pk_mul_f32 v[116:117], v[116:117], v[130:131] op_sel_hi:[1,0]
	v_cvt_pk_bf16_f32 v148, v118, v119
	v_cvt_pk_bf16_f32 v149, v120, v121
	v_cvt_pk_bf16_f32 v150, v114, v115
	v_cvt_pk_bf16_f32 v151, v116, v117
	global_store_dwordx4 v[208:209], v[148:151], off offset:256
	v_mad_i64_i32 v[208:209], vcc, s41, v177, 0
	v_lshl_add_u64 v[208:209], v[208:209], 1, v[214:215]
	v_pk_mul_f32 v[110:111], v[110:111], v[132:133] op_sel_hi:[1,0]
	v_pk_mul_f32 v[112:113], v[112:113], v[132:133] op_sel_hi:[1,0]
	v_pk_mul_f32 v[106:107], v[106:107], v[132:133] op_sel_hi:[1,0]
	v_pk_mul_f32 v[108:109], v[108:109], v[132:133] op_sel_hi:[1,0]
	v_cvt_pk_bf16_f32 v162, v110, v111
	v_cvt_pk_bf16_f32 v163, v112, v113
	v_cvt_pk_bf16_f32 v164, v106, v107
	v_cvt_pk_bf16_f32 v165, v108, v109
	global_store_dwordx4 v[208:209], v[162:165], off
	v_pk_mul_f32 v[102:103], v[102:103], v[132:133] op_sel_hi:[1,0]
	v_pk_mul_f32 v[104:105], v[104:105], v[132:133] op_sel_hi:[1,0]
	v_pk_mul_f32 v[98:99], v[98:99], v[132:133] op_sel_hi:[1,0]
	v_pk_mul_f32 v[100:101], v[100:101], v[132:133] op_sel_hi:[1,0]
	v_cvt_pk_bf16_f32 v148, v102, v103
	v_cvt_pk_bf16_f32 v149, v104, v105
	v_cvt_pk_bf16_f32 v150, v98, v99
	v_cvt_pk_bf16_f32 v151, v100, v101
	global_store_dwordx4 v[208:209], v[148:151], off offset:256
	v_mad_i64_i32 v[208:209], vcc, s41, v178, 0
	v_lshl_add_u64 v[208:209], v[208:209], 1, v[214:215]
	v_pk_mul_f32 v[94:95], v[94:95], v[134:135] op_sel_hi:[1,0]
	v_pk_mul_f32 v[96:97], v[96:97], v[134:135] op_sel_hi:[1,0]
	v_pk_mul_f32 v[90:91], v[90:91], v[134:135] op_sel_hi:[1,0]
	v_pk_mul_f32 v[92:93], v[92:93], v[134:135] op_sel_hi:[1,0]
	v_cvt_pk_bf16_f32 v162, v94, v95
	v_cvt_pk_bf16_f32 v163, v96, v97
	v_cvt_pk_bf16_f32 v164, v90, v91
	v_cvt_pk_bf16_f32 v165, v92, v93
	global_store_dwordx4 v[208:209], v[162:165], off
	v_pk_mul_f32 v[86:87], v[86:87], v[134:135] op_sel_hi:[1,0]
	v_pk_mul_f32 v[88:89], v[88:89], v[134:135] op_sel_hi:[1,0]
	v_pk_mul_f32 v[82:83], v[82:83], v[134:135] op_sel_hi:[1,0]
	v_pk_mul_f32 v[84:85], v[84:85], v[134:135] op_sel_hi:[1,0]
	v_cvt_pk_bf16_f32 v148, v86, v87
	v_cvt_pk_bf16_f32 v149, v88, v89
	v_cvt_pk_bf16_f32 v150, v82, v83
	v_cvt_pk_bf16_f32 v151, v84, v85
	global_store_dwordx4 v[208:209], v[148:151], off offset:256
	v_mad_i64_i32 v[208:209], vcc, s41, v179, 0
	v_lshl_add_u64 v[208:209], v[208:209], 1, v[214:215]
	v_pk_mul_f32 v[78:79], v[78:79], v[136:137] op_sel_hi:[1,0]
	v_pk_mul_f32 v[80:81], v[80:81], v[136:137] op_sel_hi:[1,0]
	v_pk_mul_f32 v[74:75], v[74:75], v[136:137] op_sel_hi:[1,0]
	v_pk_mul_f32 v[76:77], v[76:77], v[136:137] op_sel_hi:[1,0]
	v_cvt_pk_bf16_f32 v162, v78, v79
	v_cvt_pk_bf16_f32 v163, v80, v81
	v_cvt_pk_bf16_f32 v164, v74, v75
	v_cvt_pk_bf16_f32 v165, v76, v77
	global_store_dwordx4 v[208:209], v[162:165], off
	v_pk_mul_f32 v[70:71], v[70:71], v[136:137] op_sel_hi:[1,0]
	v_pk_mul_f32 v[72:73], v[72:73], v[136:137] op_sel_hi:[1,0]
	v_pk_mul_f32 v[66:67], v[66:67], v[136:137] op_sel_hi:[1,0]
	v_pk_mul_f32 v[68:69], v[68:69], v[136:137] op_sel_hi:[1,0]
	v_cvt_pk_bf16_f32 v148, v70, v71
	v_cvt_pk_bf16_f32 v149, v72, v73
	v_cvt_pk_bf16_f32 v150, v66, v67
	v_cvt_pk_bf16_f32 v151, v68, v69
	global_store_dwordx4 v[208:209], v[148:151], off offset:256
	v_mad_i64_i32 v[208:209], vcc, s41, v180, 0
	v_lshl_add_u64 v[208:209], v[208:209], 1, v[214:215]
	v_pk_mul_f32 v[62:63], v[62:63], v[138:139] op_sel_hi:[1,0]
	v_pk_mul_f32 v[64:65], v[64:65], v[138:139] op_sel_hi:[1,0]
	v_pk_mul_f32 v[58:59], v[58:59], v[138:139] op_sel_hi:[1,0]
	v_pk_mul_f32 v[60:61], v[60:61], v[138:139] op_sel_hi:[1,0]
	v_cvt_pk_bf16_f32 v162, v62, v63
	v_cvt_pk_bf16_f32 v163, v64, v65
	v_cvt_pk_bf16_f32 v164, v58, v59
	v_cvt_pk_bf16_f32 v165, v60, v61
	global_store_dwordx4 v[208:209], v[162:165], off
	v_pk_mul_f32 v[54:55], v[54:55], v[138:139] op_sel_hi:[1,0]
	v_pk_mul_f32 v[56:57], v[56:57], v[138:139] op_sel_hi:[1,0]
	v_pk_mul_f32 v[50:51], v[50:51], v[138:139] op_sel_hi:[1,0]
	v_pk_mul_f32 v[52:53], v[52:53], v[138:139] op_sel_hi:[1,0]
	v_cvt_pk_bf16_f32 v148, v54, v55
	v_cvt_pk_bf16_f32 v149, v56, v57
	v_cvt_pk_bf16_f32 v150, v50, v51
	v_cvt_pk_bf16_f32 v151, v52, v53
	global_store_dwordx4 v[208:209], v[148:151], off offset:256
	v_mad_i64_i32 v[208:209], vcc, s41, v181, 0
	v_lshl_add_u64 v[208:209], v[208:209], 1, v[214:215]
	v_pk_mul_f32 v[46:47], v[46:47], v[140:141] op_sel_hi:[1,0]
	v_pk_mul_f32 v[48:49], v[48:49], v[140:141] op_sel_hi:[1,0]
	v_pk_mul_f32 v[42:43], v[42:43], v[140:141] op_sel_hi:[1,0]
	v_pk_mul_f32 v[44:45], v[44:45], v[140:141] op_sel_hi:[1,0]
	v_cvt_pk_bf16_f32 v162, v46, v47
	v_cvt_pk_bf16_f32 v163, v48, v49
	v_cvt_pk_bf16_f32 v164, v42, v43
	v_cvt_pk_bf16_f32 v165, v44, v45
	global_store_dwordx4 v[208:209], v[162:165], off
	v_pk_mul_f32 v[38:39], v[38:39], v[140:141] op_sel_hi:[1,0]
	v_pk_mul_f32 v[40:41], v[40:41], v[140:141] op_sel_hi:[1,0]
	v_pk_mul_f32 v[34:35], v[34:35], v[140:141] op_sel_hi:[1,0]
	v_pk_mul_f32 v[36:37], v[36:37], v[140:141] op_sel_hi:[1,0]
	v_cvt_pk_bf16_f32 v148, v38, v39
	v_cvt_pk_bf16_f32 v149, v40, v41
	v_cvt_pk_bf16_f32 v150, v34, v35
	v_cvt_pk_bf16_f32 v151, v36, v37
	global_store_dwordx4 v[208:209], v[148:151], off offset:256
	v_mad_i64_i32 v[208:209], vcc, s41, v182, 0
	v_lshl_add_u64 v[208:209], v[208:209], 1, v[214:215]
	v_pk_mul_f32 v[30:31], v[30:31], v[142:143] op_sel_hi:[1,0]
	v_pk_mul_f32 v[32:33], v[32:33], v[142:143] op_sel_hi:[1,0]
	v_pk_mul_f32 v[26:27], v[26:27], v[142:143] op_sel_hi:[1,0]
	v_pk_mul_f32 v[28:29], v[28:29], v[142:143] op_sel_hi:[1,0]
	v_cvt_pk_bf16_f32 v162, v30, v31
	v_cvt_pk_bf16_f32 v163, v32, v33
	v_cvt_pk_bf16_f32 v164, v26, v27
	v_cvt_pk_bf16_f32 v165, v28, v29
	global_store_dwordx4 v[208:209], v[162:165], off
	v_pk_mul_f32 v[22:23], v[22:23], v[142:143] op_sel_hi:[1,0]
	v_pk_mul_f32 v[24:25], v[24:25], v[142:143] op_sel_hi:[1,0]
	v_pk_mul_f32 v[18:19], v[18:19], v[142:143] op_sel_hi:[1,0]
	v_pk_mul_f32 v[20:21], v[20:21], v[142:143] op_sel_hi:[1,0]
	v_cvt_pk_bf16_f32 v148, v22, v23
	v_cvt_pk_bf16_f32 v149, v24, v25
	v_cvt_pk_bf16_f32 v150, v18, v19
	v_cvt_pk_bf16_f32 v151, v20, v21
	global_store_dwordx4 v[208:209], v[148:151], off offset:256
	v_mad_i64_i32 v[208:209], vcc, s41, v183, 0
	v_lshl_add_u64 v[208:209], v[208:209], 1, v[214:215]
	v_pk_mul_f32 v[14:15], v[14:15], v[144:145] op_sel_hi:[1,0]
	v_pk_mul_f32 v[16:17], v[16:17], v[144:145] op_sel_hi:[1,0]
	v_pk_mul_f32 v[10:11], v[10:11], v[144:145] op_sel_hi:[1,0]
	v_pk_mul_f32 v[12:13], v[12:13], v[144:145] op_sel_hi:[1,0]
	v_cvt_pk_bf16_f32 v162, v14, v15
	v_cvt_pk_bf16_f32 v163, v16, v17
	v_cvt_pk_bf16_f32 v164, v10, v11
	v_cvt_pk_bf16_f32 v165, v12, v13
	global_store_dwordx4 v[208:209], v[162:165], off
	v_pk_mul_f32 v[6:7], v[6:7], v[144:145] op_sel_hi:[1,0]
	v_pk_mul_f32 v[8:9], v[8:9], v[144:145] op_sel_hi:[1,0]
	v_pk_mul_f32 v[2:3], v[2:3], v[144:145] op_sel_hi:[1,0]
	v_pk_mul_f32 v[4:5], v[4:5], v[144:145] op_sel_hi:[1,0]
	v_cvt_pk_bf16_f32 v148, v6, v7
	v_cvt_pk_bf16_f32 v149, v8, v9
	v_cvt_pk_bf16_f32 v150, v2, v3
	v_cvt_pk_bf16_f32 v151, v4, v5
	global_store_dwordx4 v[208:209], v[148:151], off offset:256
	s_branch .Lpj_fin
.Lpj_gelu:
	s_mov_b32 s28, 0x3d372713
	s_mov_b32 s8, 0xbfcc422a
	s_mov_b32 s26, 0x3fb8aa3b
	v_mad_i64_i32 v[208:209], vcc, s41, v176, 0
	v_lshl_add_u64 v[208:209], v[208:209], 1, v[214:215]
	v_pk_mul_f32 v[126:127], v[126:127], v[130:131] op_sel_hi:[1,0]
	v_pk_mul_f32 v[128:129], v[128:129], v[130:131] op_sel_hi:[1,0]
	v_pk_mul_f32 v[122:123], v[122:123], v[130:131] op_sel_hi:[1,0]
	v_pk_mul_f32 v[124:125], v[124:125], v[130:131] op_sel_hi:[1,0]
	v_pk_mul_f32 v[184:185], v[126:127], s[28:29] op_sel_hi:[1,0]
	v_pk_mul_f32 v[186:187], v[128:129], s[28:29] op_sel_hi:[1,0]
	v_pk_mul_f32 v[188:189], v[122:123], s[28:29] op_sel_hi:[1,0]
	v_pk_mul_f32 v[190:191], v[124:125], s[28:29] op_sel_hi:[1,0]
	v_pk_mul_f32 v[184:185], v[126:127], v[184:185]
	v_pk_mul_f32 v[186:187], v[128:129], v[186:187]
	v_pk_mul_f32 v[188:189], v[122:123], v[188:189]
	v_pk_mul_f32 v[190:191], v[124:125], v[190:191]
	v_pk_fma_f32 v[184:185], v[126:127], v[184:185], v[126:127]
	v_pk_fma_f32 v[186:187], v[128:129], v[186:187], v[128:129]
	v_pk_fma_f32 v[188:189], v[122:123], v[188:189], v[122:123]
	v_pk_fma_f32 v[190:191], v[124:125], v[190:191], v[124:125]
	v_pk_mul_f32 v[184:185], v[184:185], s[8:9] op_sel_hi:[1,0]
	v_pk_mul_f32 v[186:187], v[186:187], s[8:9] op_sel_hi:[1,0]
	v_pk_mul_f32 v[188:189], v[188:189], s[8:9] op_sel_hi:[1,0]
	v_pk_mul_f32 v[190:191], v[190:191], s[8:9] op_sel_hi:[1,0]
	v_pk_mul_f32 v[184:185], v[184:185], s[26:27] op_sel_hi:[1,0]
	v_pk_mul_f32 v[186:187], v[186:187], s[26:27] op_sel_hi:[1,0]
	v_pk_mul_f32 v[188:189], v[188:189], s[26:27] op_sel_hi:[1,0]
	v_pk_mul_f32 v[190:191], v[190:191], s[26:27] op_sel_hi:[1,0]
	v_exp_f32_e32 v184, v184
	v_exp_f32_e32 v185, v185
	v_exp_f32_e32 v186, v186
	v_exp_f32_e32 v187, v187
	v_exp_f32_e32 v188, v188
	v_exp_f32_e32 v189, v189
	v_exp_f32_e32 v190, v190
	v_exp_f32_e32 v191, v191
	v_add_f32_e32 v184, 1.0, v184
	v_add_f32_e32 v185, 1.0, v185
	v_add_f32_e32 v186, 1.0, v186
	v_add_f32_e32 v187, 1.0, v187
	v_add_f32_e32 v188, 1.0, v188
	v_add_f32_e32 v189, 1.0, v189
	v_add_f32_e32 v190, 1.0, v190
	v_add_f32_e32 v191, 1.0, v191
	v_rcp_f32_e32 v184, v184
	v_rcp_f32_e32 v185, v185
	v_rcp_f32_e32 v186, v186
	v_rcp_f32_e32 v187, v187
	v_rcp_f32_e32 v188, v188
	v_rcp_f32_e32 v189, v189
	v_rcp_f32_e32 v190, v190
	v_rcp_f32_e32 v191, v191
	s_nop 0
	v_pk_mul_f32 v[126:127], v[126:127], v[184:185]
	v_pk_mul_f32 v[128:129], v[128:129], v[186:187]
	v_pk_mul_f32 v[122:123], v[122:123], v[188:189]
	v_pk_mul_f32 v[124:125], v[124:125], v[190:191]
	v_cvt_pk_bf16_f32 v162, v126, v127
	v_cvt_pk_bf16_f32 v163, v128, v129
	v_cvt_pk_bf16_f32 v164, v122, v123
	v_cvt_pk_bf16_f32 v165, v124, v125
	global_store_dwordx4 v[208:209], v[162:165], off
	v_pk_mul_f32 v[118:119], v[118:119], v[130:131] op_sel_hi:[1,0]
	v_pk_mul_f32 v[120:121], v[120:121], v[130:131] op_sel_hi:[1,0]
	v_pk_mul_f32 v[114:115], v[114:115], v[130:131] op_sel_hi:[1,0]
	v_pk_mul_f32 v[116:117], v[116:117], v[130:131] op_sel_hi:[1,0]
	v_pk_mul_f32 v[184:185], v[118:119], s[28:29] op_sel_hi:[1,0]
	v_pk_mul_f32 v[186:187], v[120:121], s[28:29] op_sel_hi:[1,0]
	v_pk_mul_f32 v[188:189], v[114:115], s[28:29] op_sel_hi:[1,0]
	v_pk_mul_f32 v[190:191], v[116:117], s[28:29] op_sel_hi:[1,0]
	v_pk_mul_f32 v[184:185], v[118:119], v[184:185]
	v_pk_mul_f32 v[186:187], v[120:121], v[186:187]
	v_pk_mul_f32 v[188:189], v[114:115], v[188:189]
	v_pk_mul_f32 v[190:191], v[116:117], v[190:191]
	v_pk_fma_f32 v[184:185], v[118:119], v[184:185], v[118:119]
	v_pk_fma_f32 v[186:187], v[120:121], v[186:187], v[120:121]
	v_pk_fma_f32 v[188:189], v[114:115], v[188:189], v[114:115]
	v_pk_fma_f32 v[190:191], v[116:117], v[190:191], v[116:117]
	v_pk_mul_f32 v[184:185], v[184:185], s[8:9] op_sel_hi:[1,0]
	v_pk_mul_f32 v[186:187], v[186:187], s[8:9] op_sel_hi:[1,0]
	v_pk_mul_f32 v[188:189], v[188:189], s[8:9] op_sel_hi:[1,0]
	v_pk_mul_f32 v[190:191], v[190:191], s[8:9] op_sel_hi:[1,0]
	v_pk_mul_f32 v[184:185], v[184:185], s[26:27] op_sel_hi:[1,0]
	v_pk_mul_f32 v[186:187], v[186:187], s[26:27] op_sel_hi:[1,0]
	v_pk_mul_f32 v[188:189], v[188:189], s[26:27] op_sel_hi:[1,0]
	v_pk_mul_f32 v[190:191], v[190:191], s[26:27] op_sel_hi:[1,0]
	v_exp_f32_e32 v184, v184
	v_exp_f32_e32 v185, v185
	v_exp_f32_e32 v186, v186
	v_exp_f32_e32 v187, v187
	v_exp_f32_e32 v188, v188
	v_exp_f32_e32 v189, v189
	v_exp_f32_e32 v190, v190
	v_exp_f32_e32 v191, v191
	v_add_f32_e32 v184, 1.0, v184
	v_add_f32_e32 v185, 1.0, v185
	v_add_f32_e32 v186, 1.0, v186
	v_add_f32_e32 v187, 1.0, v187
	v_add_f32_e32 v188, 1.0, v188
	v_add_f32_e32 v189, 1.0, v189
	v_add_f32_e32 v190, 1.0, v190
	v_add_f32_e32 v191, 1.0, v191
	v_rcp_f32_e32 v184, v184
	v_rcp_f32_e32 v185, v185
	v_rcp_f32_e32 v186, v186
	v_rcp_f32_e32 v187, v187
	v_rcp_f32_e32 v188, v188
	v_rcp_f32_e32 v189, v189
	v_rcp_f32_e32 v190, v190
	v_rcp_f32_e32 v191, v191
	s_nop 0
	v_pk_mul_f32 v[118:119], v[118:119], v[184:185]
	v_pk_mul_f32 v[120:121], v[120:121], v[186:187]
	v_pk_mul_f32 v[114:115], v[114:115], v[188:189]
	v_pk_mul_f32 v[116:117], v[116:117], v[190:191]
	v_cvt_pk_bf16_f32 v148, v118, v119
	v_cvt_pk_bf16_f32 v149, v120, v121
	v_cvt_pk_bf16_f32 v150, v114, v115
	v_cvt_pk_bf16_f32 v151, v116, v117
	global_store_dwordx4 v[208:209], v[148:151], off offset:256
	v_mad_i64_i32 v[208:209], vcc, s41, v177, 0
	v_lshl_add_u64 v[208:209], v[208:209], 1, v[214:215]
	v_pk_mul_f32 v[110:111], v[110:111], v[132:133] op_sel_hi:[1,0]
	v_pk_mul_f32 v[112:113], v[112:113], v[132:133] op_sel_hi:[1,0]
	v_pk_mul_f32 v[106:107], v[106:107], v[132:133] op_sel_hi:[1,0]
	v_pk_mul_f32 v[108:109], v[108:109], v[132:133] op_sel_hi:[1,0]
	v_pk_mul_f32 v[184:185], v[110:111], s[28:29] op_sel_hi:[1,0]
	v_pk_mul_f32 v[186:187], v[112:113], s[28:29] op_sel_hi:[1,0]
	v_pk_mul_f32 v[188:189], v[106:107], s[28:29] op_sel_hi:[1,0]
	v_pk_mul_f32 v[190:191], v[108:109], s[28:29] op_sel_hi:[1,0]
	v_pk_mul_f32 v[184:185], v[110:111], v[184:185]
	v_pk_mul_f32 v[186:187], v[112:113], v[186:187]
	v_pk_mul_f32 v[188:189], v[106:107], v[188:189]
	v_pk_mul_f32 v[190:191], v[108:109], v[190:191]
	v_pk_fma_f32 v[184:185], v[110:111], v[184:185], v[110:111]
	v_pk_fma_f32 v[186:187], v[112:113], v[186:187], v[112:113]
	v_pk_fma_f32 v[188:189], v[106:107], v[188:189], v[106:107]
	v_pk_fma_f32 v[190:191], v[108:109], v[190:191], v[108:109]
	v_pk_mul_f32 v[184:185], v[184:185], s[8:9] op_sel_hi:[1,0]
	v_pk_mul_f32 v[186:187], v[186:187], s[8:9] op_sel_hi:[1,0]
	v_pk_mul_f32 v[188:189], v[188:189], s[8:9] op_sel_hi:[1,0]
	v_pk_mul_f32 v[190:191], v[190:191], s[8:9] op_sel_hi:[1,0]
	v_pk_mul_f32 v[184:185], v[184:185], s[26:27] op_sel_hi:[1,0]
	v_pk_mul_f32 v[186:187], v[186:187], s[26:27] op_sel_hi:[1,0]
	v_pk_mul_f32 v[188:189], v[188:189], s[26:27] op_sel_hi:[1,0]
	v_pk_mul_f32 v[190:191], v[190:191], s[26:27] op_sel_hi:[1,0]
	v_exp_f32_e32 v184, v184
	v_exp_f32_e32 v185, v185
	v_exp_f32_e32 v186, v186
	v_exp_f32_e32 v187, v187
	v_exp_f32_e32 v188, v188
	v_exp_f32_e32 v189, v189
	v_exp_f32_e32 v190, v190
	v_exp_f32_e32 v191, v191
	v_add_f32_e32 v184, 1.0, v184
	v_add_f32_e32 v185, 1.0, v185
	v_add_f32_e32 v186, 1.0, v186
	v_add_f32_e32 v187, 1.0, v187
	v_add_f32_e32 v188, 1.0, v188
	v_add_f32_e32 v189, 1.0, v189
	v_add_f32_e32 v190, 1.0, v190
	v_add_f32_e32 v191, 1.0, v191
	v_rcp_f32_e32 v184, v184
	v_rcp_f32_e32 v185, v185
	v_rcp_f32_e32 v186, v186
	v_rcp_f32_e32 v187, v187
	v_rcp_f32_e32 v188, v188
	v_rcp_f32_e32 v189, v189
	v_rcp_f32_e32 v190, v190
	v_rcp_f32_e32 v191, v191
	s_nop 0
	v_pk_mul_f32 v[110:111], v[110:111], v[184:185]
	v_pk_mul_f32 v[112:113], v[112:113], v[186:187]
	v_pk_mul_f32 v[106:107], v[106:107], v[188:189]
	v_pk_mul_f32 v[108:109], v[108:109], v[190:191]
	v_cvt_pk_bf16_f32 v162, v110, v111
	v_cvt_pk_bf16_f32 v163, v112, v113
	v_cvt_pk_bf16_f32 v164, v106, v107
	v_cvt_pk_bf16_f32 v165, v108, v109
	global_store_dwordx4 v[208:209], v[162:165], off
	v_pk_mul_f32 v[102:103], v[102:103], v[132:133] op_sel_hi:[1,0]
	v_pk_mul_f32 v[104:105], v[104:105], v[132:133] op_sel_hi:[1,0]
	v_pk_mul_f32 v[98:99], v[98:99], v[132:133] op_sel_hi:[1,0]
	v_pk_mul_f32 v[100:101], v[100:101], v[132:133] op_sel_hi:[1,0]
	v_pk_mul_f32 v[184:185], v[102:103], s[28:29] op_sel_hi:[1,0]
	v_pk_mul_f32 v[186:187], v[104:105], s[28:29] op_sel_hi:[1,0]
	v_pk_mul_f32 v[188:189], v[98:99], s[28:29] op_sel_hi:[1,0]
	v_pk_mul_f32 v[190:191], v[100:101], s[28:29] op_sel_hi:[1,0]
	v_pk_mul_f32 v[184:185], v[102:103], v[184:185]
	v_pk_mul_f32 v[186:187], v[104:105], v[186:187]
	v_pk_mul_f32 v[188:189], v[98:99], v[188:189]
	v_pk_mul_f32 v[190:191], v[100:101], v[190:191]
	v_pk_fma_f32 v[184:185], v[102:103], v[184:185], v[102:103]
	v_pk_fma_f32 v[186:187], v[104:105], v[186:187], v[104:105]
	v_pk_fma_f32 v[188:189], v[98:99], v[188:189], v[98:99]
	v_pk_fma_f32 v[190:191], v[100:101], v[190:191], v[100:101]
	v_pk_mul_f32 v[184:185], v[184:185], s[8:9] op_sel_hi:[1,0]
	v_pk_mul_f32 v[186:187], v[186:187], s[8:9] op_sel_hi:[1,0]
	v_pk_mul_f32 v[188:189], v[188:189], s[8:9] op_sel_hi:[1,0]
	v_pk_mul_f32 v[190:191], v[190:191], s[8:9] op_sel_hi:[1,0]
	v_pk_mul_f32 v[184:185], v[184:185], s[26:27] op_sel_hi:[1,0]
	v_pk_mul_f32 v[186:187], v[186:187], s[26:27] op_sel_hi:[1,0]
	v_pk_mul_f32 v[188:189], v[188:189], s[26:27] op_sel_hi:[1,0]
	v_pk_mul_f32 v[190:191], v[190:191], s[26:27] op_sel_hi:[1,0]
	v_exp_f32_e32 v184, v184
	v_exp_f32_e32 v185, v185
	v_exp_f32_e32 v186, v186
	v_exp_f32_e32 v187, v187
	v_exp_f32_e32 v188, v188
	v_exp_f32_e32 v189, v189
	v_exp_f32_e32 v190, v190
	v_exp_f32_e32 v191, v191
	v_add_f32_e32 v184, 1.0, v184
	v_add_f32_e32 v185, 1.0, v185
	v_add_f32_e32 v186, 1.0, v186
	v_add_f32_e32 v187, 1.0, v187
	v_add_f32_e32 v188, 1.0, v188
	v_add_f32_e32 v189, 1.0, v189
	v_add_f32_e32 v190, 1.0, v190
	v_add_f32_e32 v191, 1.0, v191
	v_rcp_f32_e32 v184, v184
	v_rcp_f32_e32 v185, v185
	v_rcp_f32_e32 v186, v186
	v_rcp_f32_e32 v187, v187
	v_rcp_f32_e32 v188, v188
	v_rcp_f32_e32 v189, v189
	v_rcp_f32_e32 v190, v190
	v_rcp_f32_e32 v191, v191
	s_nop 0
	v_pk_mul_f32 v[102:103], v[102:103], v[184:185]
	v_pk_mul_f32 v[104:105], v[104:105], v[186:187]
	v_pk_mul_f32 v[98:99], v[98:99], v[188:189]
	v_pk_mul_f32 v[100:101], v[100:101], v[190:191]
	v_cvt_pk_bf16_f32 v148, v102, v103
	v_cvt_pk_bf16_f32 v149, v104, v105
	v_cvt_pk_bf16_f32 v150, v98, v99
	v_cvt_pk_bf16_f32 v151, v100, v101
	global_store_dwordx4 v[208:209], v[148:151], off offset:256
	v_mad_i64_i32 v[208:209], vcc, s41, v178, 0
	v_lshl_add_u64 v[208:209], v[208:209], 1, v[214:215]
	v_pk_mul_f32 v[94:95], v[94:95], v[134:135] op_sel_hi:[1,0]
	v_pk_mul_f32 v[96:97], v[96:97], v[134:135] op_sel_hi:[1,0]
	v_pk_mul_f32 v[90:91], v[90:91], v[134:135] op_sel_hi:[1,0]
	v_pk_mul_f32 v[92:93], v[92:93], v[134:135] op_sel_hi:[1,0]
	v_pk_mul_f32 v[184:185], v[94:95], s[28:29] op_sel_hi:[1,0]
	v_pk_mul_f32 v[186:187], v[96:97], s[28:29] op_sel_hi:[1,0]
	v_pk_mul_f32 v[188:189], v[90:91], s[28:29] op_sel_hi:[1,0]
	v_pk_mul_f32 v[190:191], v[92:93], s[28:29] op_sel_hi:[1,0]
	v_pk_mul_f32 v[184:185], v[94:95], v[184:185]
	v_pk_mul_f32 v[186:187], v[96:97], v[186:187]
	v_pk_mul_f32 v[188:189], v[90:91], v[188:189]
	v_pk_mul_f32 v[190:191], v[92:93], v[190:191]
	v_pk_fma_f32 v[184:185], v[94:95], v[184:185], v[94:95]
	v_pk_fma_f32 v[186:187], v[96:97], v[186:187], v[96:97]
	v_pk_fma_f32 v[188:189], v[90:91], v[188:189], v[90:91]
	v_pk_fma_f32 v[190:191], v[92:93], v[190:191], v[92:93]
	v_pk_mul_f32 v[184:185], v[184:185], s[8:9] op_sel_hi:[1,0]
	v_pk_mul_f32 v[186:187], v[186:187], s[8:9] op_sel_hi:[1,0]
	v_pk_mul_f32 v[188:189], v[188:189], s[8:9] op_sel_hi:[1,0]
	v_pk_mul_f32 v[190:191], v[190:191], s[8:9] op_sel_hi:[1,0]
	v_pk_mul_f32 v[184:185], v[184:185], s[26:27] op_sel_hi:[1,0]
	v_pk_mul_f32 v[186:187], v[186:187], s[26:27] op_sel_hi:[1,0]
	v_pk_mul_f32 v[188:189], v[188:189], s[26:27] op_sel_hi:[1,0]
	v_pk_mul_f32 v[190:191], v[190:191], s[26:27] op_sel_hi:[1,0]
	v_exp_f32_e32 v184, v184
	v_exp_f32_e32 v185, v185
	v_exp_f32_e32 v186, v186
	v_exp_f32_e32 v187, v187
	v_exp_f32_e32 v188, v188
	v_exp_f32_e32 v189, v189
	v_exp_f32_e32 v190, v190
	v_exp_f32_e32 v191, v191
	v_add_f32_e32 v184, 1.0, v184
	v_add_f32_e32 v185, 1.0, v185
	v_add_f32_e32 v186, 1.0, v186
	v_add_f32_e32 v187, 1.0, v187
	v_add_f32_e32 v188, 1.0, v188
	v_add_f32_e32 v189, 1.0, v189
	v_add_f32_e32 v190, 1.0, v190
	v_add_f32_e32 v191, 1.0, v191
	v_rcp_f32_e32 v184, v184
	v_rcp_f32_e32 v185, v185
	v_rcp_f32_e32 v186, v186
	v_rcp_f32_e32 v187, v187
	v_rcp_f32_e32 v188, v188
	v_rcp_f32_e32 v189, v189
	v_rcp_f32_e32 v190, v190
	v_rcp_f32_e32 v191, v191
	s_nop 0
	v_pk_mul_f32 v[94:95], v[94:95], v[184:185]
	v_pk_mul_f32 v[96:97], v[96:97], v[186:187]
	v_pk_mul_f32 v[90:91], v[90:91], v[188:189]
	v_pk_mul_f32 v[92:93], v[92:93], v[190:191]
	v_cvt_pk_bf16_f32 v162, v94, v95
	v_cvt_pk_bf16_f32 v163, v96, v97
	v_cvt_pk_bf16_f32 v164, v90, v91
	v_cvt_pk_bf16_f32 v165, v92, v93
	global_store_dwordx4 v[208:209], v[162:165], off
	v_pk_mul_f32 v[86:87], v[86:87], v[134:135] op_sel_hi:[1,0]
	v_pk_mul_f32 v[88:89], v[88:89], v[134:135] op_sel_hi:[1,0]
	v_pk_mul_f32 v[82:83], v[82:83], v[134:135] op_sel_hi:[1,0]
	v_pk_mul_f32 v[84:85], v[84:85], v[134:135] op_sel_hi:[1,0]
	v_pk_mul_f32 v[184:185], v[86:87], s[28:29] op_sel_hi:[1,0]
	v_pk_mul_f32 v[186:187], v[88:89], s[28:29] op_sel_hi:[1,0]
	v_pk_mul_f32 v[188:189], v[82:83], s[28:29] op_sel_hi:[1,0]
	v_pk_mul_f32 v[190:191], v[84:85], s[28:29] op_sel_hi:[1,0]
	v_pk_mul_f32 v[184:185], v[86:87], v[184:185]
	v_pk_mul_f32 v[186:187], v[88:89], v[186:187]
	v_pk_mul_f32 v[188:189], v[82:83], v[188:189]
	v_pk_mul_f32 v[190:191], v[84:85], v[190:191]
	v_pk_fma_f32 v[184:185], v[86:87], v[184:185], v[86:87]
	v_pk_fma_f32 v[186:187], v[88:89], v[186:187], v[88:89]
	v_pk_fma_f32 v[188:189], v[82:83], v[188:189], v[82:83]
	v_pk_fma_f32 v[190:191], v[84:85], v[190:191], v[84:85]
	v_pk_mul_f32 v[184:185], v[184:185], s[8:9] op_sel_hi:[1,0]
	v_pk_mul_f32 v[186:187], v[186:187], s[8:9] op_sel_hi:[1,0]
	v_pk_mul_f32 v[188:189], v[188:189], s[8:9] op_sel_hi:[1,0]
	v_pk_mul_f32 v[190:191], v[190:191], s[8:9] op_sel_hi:[1,0]
	v_pk_mul_f32 v[184:185], v[184:185], s[26:27] op_sel_hi:[1,0]
	v_pk_mul_f32 v[186:187], v[186:187], s[26:27] op_sel_hi:[1,0]
	v_pk_mul_f32 v[188:189], v[188:189], s[26:27] op_sel_hi:[1,0]
	v_pk_mul_f32 v[190:191], v[190:191], s[26:27] op_sel_hi:[1,0]
	v_exp_f32_e32 v184, v184
	v_exp_f32_e32 v185, v185
	v_exp_f32_e32 v186, v186
	v_exp_f32_e32 v187, v187
	v_exp_f32_e32 v188, v188
	v_exp_f32_e32 v189, v189
	v_exp_f32_e32 v190, v190
	v_exp_f32_e32 v191, v191
	v_add_f32_e32 v184, 1.0, v184
	v_add_f32_e32 v185, 1.0, v185
	v_add_f32_e32 v186, 1.0, v186
	v_add_f32_e32 v187, 1.0, v187
	v_add_f32_e32 v188, 1.0, v188
	v_add_f32_e32 v189, 1.0, v189
	v_add_f32_e32 v190, 1.0, v190
	v_add_f32_e32 v191, 1.0, v191
	v_rcp_f32_e32 v184, v184
	v_rcp_f32_e32 v185, v185
	v_rcp_f32_e32 v186, v186
	v_rcp_f32_e32 v187, v187
	v_rcp_f32_e32 v188, v188
	v_rcp_f32_e32 v189, v189
	v_rcp_f32_e32 v190, v190
	v_rcp_f32_e32 v191, v191
	s_nop 0
	v_pk_mul_f32 v[86:87], v[86:87], v[184:185]
	v_pk_mul_f32 v[88:89], v[88:89], v[186:187]
	v_pk_mul_f32 v[82:83], v[82:83], v[188:189]
	v_pk_mul_f32 v[84:85], v[84:85], v[190:191]
	v_cvt_pk_bf16_f32 v148, v86, v87
	v_cvt_pk_bf16_f32 v149, v88, v89
	v_cvt_pk_bf16_f32 v150, v82, v83
	v_cvt_pk_bf16_f32 v151, v84, v85
	global_store_dwordx4 v[208:209], v[148:151], off offset:256
	v_mad_i64_i32 v[208:209], vcc, s41, v179, 0
	v_lshl_add_u64 v[208:209], v[208:209], 1, v[214:215]
	v_pk_mul_f32 v[78:79], v[78:79], v[136:137] op_sel_hi:[1,0]
	v_pk_mul_f32 v[80:81], v[80:81], v[136:137] op_sel_hi:[1,0]
	v_pk_mul_f32 v[74:75], v[74:75], v[136:137] op_sel_hi:[1,0]
	v_pk_mul_f32 v[76:77], v[76:77], v[136:137] op_sel_hi:[1,0]
	v_pk_mul_f32 v[184:185], v[78:79], s[28:29] op_sel_hi:[1,0]
	v_pk_mul_f32 v[186:187], v[80:81], s[28:29] op_sel_hi:[1,0]
	v_pk_mul_f32 v[188:189], v[74:75], s[28:29] op_sel_hi:[1,0]
	v_pk_mul_f32 v[190:191], v[76:77], s[28:29] op_sel_hi:[1,0]
	v_pk_mul_f32 v[184:185], v[78:79], v[184:185]
	v_pk_mul_f32 v[186:187], v[80:81], v[186:187]
	v_pk_mul_f32 v[188:189], v[74:75], v[188:189]
	v_pk_mul_f32 v[190:191], v[76:77], v[190:191]
	v_pk_fma_f32 v[184:185], v[78:79], v[184:185], v[78:79]
	v_pk_fma_f32 v[186:187], v[80:81], v[186:187], v[80:81]
	v_pk_fma_f32 v[188:189], v[74:75], v[188:189], v[74:75]
	v_pk_fma_f32 v[190:191], v[76:77], v[190:191], v[76:77]
	v_pk_mul_f32 v[184:185], v[184:185], s[8:9] op_sel_hi:[1,0]
	v_pk_mul_f32 v[186:187], v[186:187], s[8:9] op_sel_hi:[1,0]
	v_pk_mul_f32 v[188:189], v[188:189], s[8:9] op_sel_hi:[1,0]
	v_pk_mul_f32 v[190:191], v[190:191], s[8:9] op_sel_hi:[1,0]
	v_pk_mul_f32 v[184:185], v[184:185], s[26:27] op_sel_hi:[1,0]
	v_pk_mul_f32 v[186:187], v[186:187], s[26:27] op_sel_hi:[1,0]
	v_pk_mul_f32 v[188:189], v[188:189], s[26:27] op_sel_hi:[1,0]
	v_pk_mul_f32 v[190:191], v[190:191], s[26:27] op_sel_hi:[1,0]
	v_exp_f32_e32 v184, v184
	v_exp_f32_e32 v185, v185
	v_exp_f32_e32 v186, v186
	v_exp_f32_e32 v187, v187
	v_exp_f32_e32 v188, v188
	v_exp_f32_e32 v189, v189
	v_exp_f32_e32 v190, v190
	v_exp_f32_e32 v191, v191
	v_add_f32_e32 v184, 1.0, v184
	v_add_f32_e32 v185, 1.0, v185
	v_add_f32_e32 v186, 1.0, v186
	v_add_f32_e32 v187, 1.0, v187
	v_add_f32_e32 v188, 1.0, v188
	v_add_f32_e32 v189, 1.0, v189
	v_add_f32_e32 v190, 1.0, v190
	v_add_f32_e32 v191, 1.0, v191
	v_rcp_f32_e32 v184, v184
	v_rcp_f32_e32 v185, v185
	v_rcp_f32_e32 v186, v186
	v_rcp_f32_e32 v187, v187
	v_rcp_f32_e32 v188, v188
	v_rcp_f32_e32 v189, v189
	v_rcp_f32_e32 v190, v190
	v_rcp_f32_e32 v191, v191
	s_nop 0
	v_pk_mul_f32 v[78:79], v[78:79], v[184:185]
	v_pk_mul_f32 v[80:81], v[80:81], v[186:187]
	v_pk_mul_f32 v[74:75], v[74:75], v[188:189]
	v_pk_mul_f32 v[76:77], v[76:77], v[190:191]
	v_cvt_pk_bf16_f32 v162, v78, v79
	v_cvt_pk_bf16_f32 v163, v80, v81
	v_cvt_pk_bf16_f32 v164, v74, v75
	v_cvt_pk_bf16_f32 v165, v76, v77
	global_store_dwordx4 v[208:209], v[162:165], off
	v_pk_mul_f32 v[70:71], v[70:71], v[136:137] op_sel_hi:[1,0]
	v_pk_mul_f32 v[72:73], v[72:73], v[136:137] op_sel_hi:[1,0]
	v_pk_mul_f32 v[66:67], v[66:67], v[136:137] op_sel_hi:[1,0]
	v_pk_mul_f32 v[68:69], v[68:69], v[136:137] op_sel_hi:[1,0]
	v_pk_mul_f32 v[184:185], v[70:71], s[28:29] op_sel_hi:[1,0]
	v_pk_mul_f32 v[186:187], v[72:73], s[28:29] op_sel_hi:[1,0]
	v_pk_mul_f32 v[188:189], v[66:67], s[28:29] op_sel_hi:[1,0]
	v_pk_mul_f32 v[190:191], v[68:69], s[28:29] op_sel_hi:[1,0]
	v_pk_mul_f32 v[184:185], v[70:71], v[184:185]
	v_pk_mul_f32 v[186:187], v[72:73], v[186:187]
	v_pk_mul_f32 v[188:189], v[66:67], v[188:189]
	v_pk_mul_f32 v[190:191], v[68:69], v[190:191]
	v_pk_fma_f32 v[184:185], v[70:71], v[184:185], v[70:71]
	v_pk_fma_f32 v[186:187], v[72:73], v[186:187], v[72:73]
	v_pk_fma_f32 v[188:189], v[66:67], v[188:189], v[66:67]
	v_pk_fma_f32 v[190:191], v[68:69], v[190:191], v[68:69]
	v_pk_mul_f32 v[184:185], v[184:185], s[8:9] op_sel_hi:[1,0]
	v_pk_mul_f32 v[186:187], v[186:187], s[8:9] op_sel_hi:[1,0]
	v_pk_mul_f32 v[188:189], v[188:189], s[8:9] op_sel_hi:[1,0]
	v_pk_mul_f32 v[190:191], v[190:191], s[8:9] op_sel_hi:[1,0]
	v_pk_mul_f32 v[184:185], v[184:185], s[26:27] op_sel_hi:[1,0]
	v_pk_mul_f32 v[186:187], v[186:187], s[26:27] op_sel_hi:[1,0]
	v_pk_mul_f32 v[188:189], v[188:189], s[26:27] op_sel_hi:[1,0]
	v_pk_mul_f32 v[190:191], v[190:191], s[26:27] op_sel_hi:[1,0]
	v_exp_f32_e32 v184, v184
	v_exp_f32_e32 v185, v185
	v_exp_f32_e32 v186, v186
	v_exp_f32_e32 v187, v187
	v_exp_f32_e32 v188, v188
	v_exp_f32_e32 v189, v189
	v_exp_f32_e32 v190, v190
	v_exp_f32_e32 v191, v191
	v_add_f32_e32 v184, 1.0, v184
	v_add_f32_e32 v185, 1.0, v185
	v_add_f32_e32 v186, 1.0, v186
	v_add_f32_e32 v187, 1.0, v187
	v_add_f32_e32 v188, 1.0, v188
	v_add_f32_e32 v189, 1.0, v189
	v_add_f32_e32 v190, 1.0, v190
	v_add_f32_e32 v191, 1.0, v191
	v_rcp_f32_e32 v184, v184
	v_rcp_f32_e32 v185, v185
	v_rcp_f32_e32 v186, v186
	v_rcp_f32_e32 v187, v187
	v_rcp_f32_e32 v188, v188
	v_rcp_f32_e32 v189, v189
	v_rcp_f32_e32 v190, v190
	v_rcp_f32_e32 v191, v191
	s_nop 0
	v_pk_mul_f32 v[70:71], v[70:71], v[184:185]
	v_pk_mul_f32 v[72:73], v[72:73], v[186:187]
	v_pk_mul_f32 v[66:67], v[66:67], v[188:189]
	v_pk_mul_f32 v[68:69], v[68:69], v[190:191]
	v_cvt_pk_bf16_f32 v148, v70, v71
	v_cvt_pk_bf16_f32 v149, v72, v73
	v_cvt_pk_bf16_f32 v150, v66, v67
	v_cvt_pk_bf16_f32 v151, v68, v69
	global_store_dwordx4 v[208:209], v[148:151], off offset:256
	v_mad_i64_i32 v[208:209], vcc, s41, v180, 0
	v_lshl_add_u64 v[208:209], v[208:209], 1, v[214:215]
	v_pk_mul_f32 v[62:63], v[62:63], v[138:139] op_sel_hi:[1,0]
	v_pk_mul_f32 v[64:65], v[64:65], v[138:139] op_sel_hi:[1,0]
	v_pk_mul_f32 v[58:59], v[58:59], v[138:139] op_sel_hi:[1,0]
	v_pk_mul_f32 v[60:61], v[60:61], v[138:139] op_sel_hi:[1,0]
	v_pk_mul_f32 v[184:185], v[62:63], s[28:29] op_sel_hi:[1,0]
	v_pk_mul_f32 v[186:187], v[64:65], s[28:29] op_sel_hi:[1,0]
	v_pk_mul_f32 v[188:189], v[58:59], s[28:29] op_sel_hi:[1,0]
	v_pk_mul_f32 v[190:191], v[60:61], s[28:29] op_sel_hi:[1,0]
	v_pk_mul_f32 v[184:185], v[62:63], v[184:185]
	v_pk_mul_f32 v[186:187], v[64:65], v[186:187]
	v_pk_mul_f32 v[188:189], v[58:59], v[188:189]
	v_pk_mul_f32 v[190:191], v[60:61], v[190:191]
	v_pk_fma_f32 v[184:185], v[62:63], v[184:185], v[62:63]
	v_pk_fma_f32 v[186:187], v[64:65], v[186:187], v[64:65]
	v_pk_fma_f32 v[188:189], v[58:59], v[188:189], v[58:59]
	v_pk_fma_f32 v[190:191], v[60:61], v[190:191], v[60:61]
	v_pk_mul_f32 v[184:185], v[184:185], s[8:9] op_sel_hi:[1,0]
	v_pk_mul_f32 v[186:187], v[186:187], s[8:9] op_sel_hi:[1,0]
	v_pk_mul_f32 v[188:189], v[188:189], s[8:9] op_sel_hi:[1,0]
	v_pk_mul_f32 v[190:191], v[190:191], s[8:9] op_sel_hi:[1,0]
	v_pk_mul_f32 v[184:185], v[184:185], s[26:27] op_sel_hi:[1,0]
	v_pk_mul_f32 v[186:187], v[186:187], s[26:27] op_sel_hi:[1,0]
	v_pk_mul_f32 v[188:189], v[188:189], s[26:27] op_sel_hi:[1,0]
	v_pk_mul_f32 v[190:191], v[190:191], s[26:27] op_sel_hi:[1,0]
	v_exp_f32_e32 v184, v184
	v_exp_f32_e32 v185, v185
	v_exp_f32_e32 v186, v186
	v_exp_f32_e32 v187, v187
	v_exp_f32_e32 v188, v188
	v_exp_f32_e32 v189, v189
	v_exp_f32_e32 v190, v190
	v_exp_f32_e32 v191, v191
	v_add_f32_e32 v184, 1.0, v184
	v_add_f32_e32 v185, 1.0, v185
	v_add_f32_e32 v186, 1.0, v186
	v_add_f32_e32 v187, 1.0, v187
	v_add_f32_e32 v188, 1.0, v188
	v_add_f32_e32 v189, 1.0, v189
	v_add_f32_e32 v190, 1.0, v190
	v_add_f32_e32 v191, 1.0, v191
	v_rcp_f32_e32 v184, v184
	v_rcp_f32_e32 v185, v185
	v_rcp_f32_e32 v186, v186
	v_rcp_f32_e32 v187, v187
	v_rcp_f32_e32 v188, v188
	v_rcp_f32_e32 v189, v189
	v_rcp_f32_e32 v190, v190
	v_rcp_f32_e32 v191, v191
	s_nop 0
	v_pk_mul_f32 v[62:63], v[62:63], v[184:185]
	v_pk_mul_f32 v[64:65], v[64:65], v[186:187]
	v_pk_mul_f32 v[58:59], v[58:59], v[188:189]
	v_pk_mul_f32 v[60:61], v[60:61], v[190:191]
	v_cvt_pk_bf16_f32 v162, v62, v63
	v_cvt_pk_bf16_f32 v163, v64, v65
	v_cvt_pk_bf16_f32 v164, v58, v59
	v_cvt_pk_bf16_f32 v165, v60, v61
	global_store_dwordx4 v[208:209], v[162:165], off
	v_pk_mul_f32 v[54:55], v[54:55], v[138:139] op_sel_hi:[1,0]
	v_pk_mul_f32 v[56:57], v[56:57], v[138:139] op_sel_hi:[1,0]
	v_pk_mul_f32 v[50:51], v[50:51], v[138:139] op_sel_hi:[1,0]
	v_pk_mul_f32 v[52:53], v[52:53], v[138:139] op_sel_hi:[1,0]
	v_pk_mul_f32 v[184:185], v[54:55], s[28:29] op_sel_hi:[1,0]
	v_pk_mul_f32 v[186:187], v[56:57], s[28:29] op_sel_hi:[1,0]
	v_pk_mul_f32 v[188:189], v[50:51], s[28:29] op_sel_hi:[1,0]
	v_pk_mul_f32 v[190:191], v[52:53], s[28:29] op_sel_hi:[1,0]
	v_pk_mul_f32 v[184:185], v[54:55], v[184:185]
	v_pk_mul_f32 v[186:187], v[56:57], v[186:187]
	v_pk_mul_f32 v[188:189], v[50:51], v[188:189]
	v_pk_mul_f32 v[190:191], v[52:53], v[190:191]
	v_pk_fma_f32 v[184:185], v[54:55], v[184:185], v[54:55]
	v_pk_fma_f32 v[186:187], v[56:57], v[186:187], v[56:57]
	v_pk_fma_f32 v[188:189], v[50:51], v[188:189], v[50:51]
	v_pk_fma_f32 v[190:191], v[52:53], v[190:191], v[52:53]
	v_pk_mul_f32 v[184:185], v[184:185], s[8:9] op_sel_hi:[1,0]
	v_pk_mul_f32 v[186:187], v[186:187], s[8:9] op_sel_hi:[1,0]
	v_pk_mul_f32 v[188:189], v[188:189], s[8:9] op_sel_hi:[1,0]
	v_pk_mul_f32 v[190:191], v[190:191], s[8:9] op_sel_hi:[1,0]
	v_pk_mul_f32 v[184:185], v[184:185], s[26:27] op_sel_hi:[1,0]
	v_pk_mul_f32 v[186:187], v[186:187], s[26:27] op_sel_hi:[1,0]
	v_pk_mul_f32 v[188:189], v[188:189], s[26:27] op_sel_hi:[1,0]
	v_pk_mul_f32 v[190:191], v[190:191], s[26:27] op_sel_hi:[1,0]
	v_exp_f32_e32 v184, v184
	v_exp_f32_e32 v185, v185
	v_exp_f32_e32 v186, v186
	v_exp_f32_e32 v187, v187
	v_exp_f32_e32 v188, v188
	v_exp_f32_e32 v189, v189
	v_exp_f32_e32 v190, v190
	v_exp_f32_e32 v191, v191
	v_add_f32_e32 v184, 1.0, v184
	v_add_f32_e32 v185, 1.0, v185
	v_add_f32_e32 v186, 1.0, v186
	v_add_f32_e32 v187, 1.0, v187
	v_add_f32_e32 v188, 1.0, v188
	v_add_f32_e32 v189, 1.0, v189
	v_add_f32_e32 v190, 1.0, v190
	v_add_f32_e32 v191, 1.0, v191
	v_rcp_f32_e32 v184, v184
	v_rcp_f32_e32 v185, v185
	v_rcp_f32_e32 v186, v186
	v_rcp_f32_e32 v187, v187
	v_rcp_f32_e32 v188, v188
	v_rcp_f32_e32 v189, v189
	v_rcp_f32_e32 v190, v190
	v_rcp_f32_e32 v191, v191
	s_nop 0
	v_pk_mul_f32 v[54:55], v[54:55], v[184:185]
	v_pk_mul_f32 v[56:57], v[56:57], v[186:187]
	v_pk_mul_f32 v[50:51], v[50:51], v[188:189]
	v_pk_mul_f32 v[52:53], v[52:53], v[190:191]
	v_cvt_pk_bf16_f32 v148, v54, v55
	v_cvt_pk_bf16_f32 v149, v56, v57
	v_cvt_pk_bf16_f32 v150, v50, v51
	v_cvt_pk_bf16_f32 v151, v52, v53
	global_store_dwordx4 v[208:209], v[148:151], off offset:256
	v_mad_i64_i32 v[208:209], vcc, s41, v181, 0
	v_lshl_add_u64 v[208:209], v[208:209], 1, v[214:215]
	v_pk_mul_f32 v[46:47], v[46:47], v[140:141] op_sel_hi:[1,0]
	v_pk_mul_f32 v[48:49], v[48:49], v[140:141] op_sel_hi:[1,0]
	v_pk_mul_f32 v[42:43], v[42:43], v[140:141] op_sel_hi:[1,0]
	v_pk_mul_f32 v[44:45], v[44:45], v[140:141] op_sel_hi:[1,0]
	v_pk_mul_f32 v[184:185], v[46:47], s[28:29] op_sel_hi:[1,0]
	v_pk_mul_f32 v[186:187], v[48:49], s[28:29] op_sel_hi:[1,0]
	v_pk_mul_f32 v[188:189], v[42:43], s[28:29] op_sel_hi:[1,0]
	v_pk_mul_f32 v[190:191], v[44:45], s[28:29] op_sel_hi:[1,0]
	v_pk_mul_f32 v[184:185], v[46:47], v[184:185]
	v_pk_mul_f32 v[186:187], v[48:49], v[186:187]
	v_pk_mul_f32 v[188:189], v[42:43], v[188:189]
	v_pk_mul_f32 v[190:191], v[44:45], v[190:191]
	v_pk_fma_f32 v[184:185], v[46:47], v[184:185], v[46:47]
	v_pk_fma_f32 v[186:187], v[48:49], v[186:187], v[48:49]
	v_pk_fma_f32 v[188:189], v[42:43], v[188:189], v[42:43]
	v_pk_fma_f32 v[190:191], v[44:45], v[190:191], v[44:45]
	v_pk_mul_f32 v[184:185], v[184:185], s[8:9] op_sel_hi:[1,0]
	v_pk_mul_f32 v[186:187], v[186:187], s[8:9] op_sel_hi:[1,0]
	v_pk_mul_f32 v[188:189], v[188:189], s[8:9] op_sel_hi:[1,0]
	v_pk_mul_f32 v[190:191], v[190:191], s[8:9] op_sel_hi:[1,0]
	v_pk_mul_f32 v[184:185], v[184:185], s[26:27] op_sel_hi:[1,0]
	v_pk_mul_f32 v[186:187], v[186:187], s[26:27] op_sel_hi:[1,0]
	v_pk_mul_f32 v[188:189], v[188:189], s[26:27] op_sel_hi:[1,0]
	v_pk_mul_f32 v[190:191], v[190:191], s[26:27] op_sel_hi:[1,0]
	v_exp_f32_e32 v184, v184
	v_exp_f32_e32 v185, v185
	v_exp_f32_e32 v186, v186
	v_exp_f32_e32 v187, v187
	v_exp_f32_e32 v188, v188
	v_exp_f32_e32 v189, v189
	v_exp_f32_e32 v190, v190
	v_exp_f32_e32 v191, v191
	v_add_f32_e32 v184, 1.0, v184
	v_add_f32_e32 v185, 1.0, v185
	v_add_f32_e32 v186, 1.0, v186
	v_add_f32_e32 v187, 1.0, v187
	v_add_f32_e32 v188, 1.0, v188
	v_add_f32_e32 v189, 1.0, v189
	v_add_f32_e32 v190, 1.0, v190
	v_add_f32_e32 v191, 1.0, v191
	v_rcp_f32_e32 v184, v184
	v_rcp_f32_e32 v185, v185
	v_rcp_f32_e32 v186, v186
	v_rcp_f32_e32 v187, v187
	v_rcp_f32_e32 v188, v188
	v_rcp_f32_e32 v189, v189
	v_rcp_f32_e32 v190, v190
	v_rcp_f32_e32 v191, v191
	s_nop 0
	v_pk_mul_f32 v[46:47], v[46:47], v[184:185]
	v_pk_mul_f32 v[48:49], v[48:49], v[186:187]
	v_pk_mul_f32 v[42:43], v[42:43], v[188:189]
	v_pk_mul_f32 v[44:45], v[44:45], v[190:191]
	v_cvt_pk_bf16_f32 v162, v46, v47
	v_cvt_pk_bf16_f32 v163, v48, v49
	v_cvt_pk_bf16_f32 v164, v42, v43
	v_cvt_pk_bf16_f32 v165, v44, v45
	global_store_dwordx4 v[208:209], v[162:165], off
	v_pk_mul_f32 v[38:39], v[38:39], v[140:141] op_sel_hi:[1,0]
	v_pk_mul_f32 v[40:41], v[40:41], v[140:141] op_sel_hi:[1,0]
	v_pk_mul_f32 v[34:35], v[34:35], v[140:141] op_sel_hi:[1,0]
	v_pk_mul_f32 v[36:37], v[36:37], v[140:141] op_sel_hi:[1,0]
	v_pk_mul_f32 v[184:185], v[38:39], s[28:29] op_sel_hi:[1,0]
	v_pk_mul_f32 v[186:187], v[40:41], s[28:29] op_sel_hi:[1,0]
	v_pk_mul_f32 v[188:189], v[34:35], s[28:29] op_sel_hi:[1,0]
	v_pk_mul_f32 v[190:191], v[36:37], s[28:29] op_sel_hi:[1,0]
	v_pk_mul_f32 v[184:185], v[38:39], v[184:185]
	v_pk_mul_f32 v[186:187], v[40:41], v[186:187]
	v_pk_mul_f32 v[188:189], v[34:35], v[188:189]
	v_pk_mul_f32 v[190:191], v[36:37], v[190:191]
	v_pk_fma_f32 v[184:185], v[38:39], v[184:185], v[38:39]
	v_pk_fma_f32 v[186:187], v[40:41], v[186:187], v[40:41]
	v_pk_fma_f32 v[188:189], v[34:35], v[188:189], v[34:35]
	v_pk_fma_f32 v[190:191], v[36:37], v[190:191], v[36:37]
	v_pk_mul_f32 v[184:185], v[184:185], s[8:9] op_sel_hi:[1,0]
	v_pk_mul_f32 v[186:187], v[186:187], s[8:9] op_sel_hi:[1,0]
	v_pk_mul_f32 v[188:189], v[188:189], s[8:9] op_sel_hi:[1,0]
	v_pk_mul_f32 v[190:191], v[190:191], s[8:9] op_sel_hi:[1,0]
	v_pk_mul_f32 v[184:185], v[184:185], s[26:27] op_sel_hi:[1,0]
	v_pk_mul_f32 v[186:187], v[186:187], s[26:27] op_sel_hi:[1,0]
	v_pk_mul_f32 v[188:189], v[188:189], s[26:27] op_sel_hi:[1,0]
	v_pk_mul_f32 v[190:191], v[190:191], s[26:27] op_sel_hi:[1,0]
	v_exp_f32_e32 v184, v184
	v_exp_f32_e32 v185, v185
	v_exp_f32_e32 v186, v186
	v_exp_f32_e32 v187, v187
	v_exp_f32_e32 v188, v188
	v_exp_f32_e32 v189, v189
	v_exp_f32_e32 v190, v190
	v_exp_f32_e32 v191, v191
	v_add_f32_e32 v184, 1.0, v184
	v_add_f32_e32 v185, 1.0, v185
	v_add_f32_e32 v186, 1.0, v186
	v_add_f32_e32 v187, 1.0, v187
	v_add_f32_e32 v188, 1.0, v188
	v_add_f32_e32 v189, 1.0, v189
	v_add_f32_e32 v190, 1.0, v190
	v_add_f32_e32 v191, 1.0, v191
	v_rcp_f32_e32 v184, v184
	v_rcp_f32_e32 v185, v185
	v_rcp_f32_e32 v186, v186
	v_rcp_f32_e32 v187, v187
	v_rcp_f32_e32 v188, v188
	v_rcp_f32_e32 v189, v189
	v_rcp_f32_e32 v190, v190
	v_rcp_f32_e32 v191, v191
	s_nop 0
	v_pk_mul_f32 v[38:39], v[38:39], v[184:185]
	v_pk_mul_f32 v[40:41], v[40:41], v[186:187]
	v_pk_mul_f32 v[34:35], v[34:35], v[188:189]
	v_pk_mul_f32 v[36:37], v[36:37], v[190:191]
	v_cvt_pk_bf16_f32 v148, v38, v39
	v_cvt_pk_bf16_f32 v149, v40, v41
	v_cvt_pk_bf16_f32 v150, v34, v35
	v_cvt_pk_bf16_f32 v151, v36, v37
	global_store_dwordx4 v[208:209], v[148:151], off offset:256
	v_mad_i64_i32 v[208:209], vcc, s41, v182, 0
	v_lshl_add_u64 v[208:209], v[208:209], 1, v[214:215]
	v_pk_mul_f32 v[30:31], v[30:31], v[142:143] op_sel_hi:[1,0]
	v_pk_mul_f32 v[32:33], v[32:33], v[142:143] op_sel_hi:[1,0]
	v_pk_mul_f32 v[26:27], v[26:27], v[142:143] op_sel_hi:[1,0]
	v_pk_mul_f32 v[28:29], v[28:29], v[142:143] op_sel_hi:[1,0]
	v_pk_mul_f32 v[184:185], v[30:31], s[28:29] op_sel_hi:[1,0]
	v_pk_mul_f32 v[186:187], v[32:33], s[28:29] op_sel_hi:[1,0]
	v_pk_mul_f32 v[188:189], v[26:27], s[28:29] op_sel_hi:[1,0]
	v_pk_mul_f32 v[190:191], v[28:29], s[28:29] op_sel_hi:[1,0]
	v_pk_mul_f32 v[184:185], v[30:31], v[184:185]
	v_pk_mul_f32 v[186:187], v[32:33], v[186:187]
	v_pk_mul_f32 v[188:189], v[26:27], v[188:189]
	v_pk_mul_f32 v[190:191], v[28:29], v[190:191]
	v_pk_fma_f32 v[184:185], v[30:31], v[184:185], v[30:31]
	v_pk_fma_f32 v[186:187], v[32:33], v[186:187], v[32:33]
	v_pk_fma_f32 v[188:189], v[26:27], v[188:189], v[26:27]
	v_pk_fma_f32 v[190:191], v[28:29], v[190:191], v[28:29]
	v_pk_mul_f32 v[184:185], v[184:185], s[8:9] op_sel_hi:[1,0]
	v_pk_mul_f32 v[186:187], v[186:187], s[8:9] op_sel_hi:[1,0]
	v_pk_mul_f32 v[188:189], v[188:189], s[8:9] op_sel_hi:[1,0]
	v_pk_mul_f32 v[190:191], v[190:191], s[8:9] op_sel_hi:[1,0]
	v_pk_mul_f32 v[184:185], v[184:185], s[26:27] op_sel_hi:[1,0]
	v_pk_mul_f32 v[186:187], v[186:187], s[26:27] op_sel_hi:[1,0]
	v_pk_mul_f32 v[188:189], v[188:189], s[26:27] op_sel_hi:[1,0]
	v_pk_mul_f32 v[190:191], v[190:191], s[26:27] op_sel_hi:[1,0]
	v_exp_f32_e32 v184, v184
	v_exp_f32_e32 v185, v185
	v_exp_f32_e32 v186, v186
	v_exp_f32_e32 v187, v187
	v_exp_f32_e32 v188, v188
	v_exp_f32_e32 v189, v189
	v_exp_f32_e32 v190, v190
	v_exp_f32_e32 v191, v191
	v_add_f32_e32 v184, 1.0, v184
	v_add_f32_e32 v185, 1.0, v185
	v_add_f32_e32 v186, 1.0, v186
	v_add_f32_e32 v187, 1.0, v187
	v_add_f32_e32 v188, 1.0, v188
	v_add_f32_e32 v189, 1.0, v189
	v_add_f32_e32 v190, 1.0, v190
	v_add_f32_e32 v191, 1.0, v191
	v_rcp_f32_e32 v184, v184
	v_rcp_f32_e32 v185, v185
	v_rcp_f32_e32 v186, v186
	v_rcp_f32_e32 v187, v187
	v_rcp_f32_e32 v188, v188
	v_rcp_f32_e32 v189, v189
	v_rcp_f32_e32 v190, v190
	v_rcp_f32_e32 v191, v191
	s_nop 0
	v_pk_mul_f32 v[30:31], v[30:31], v[184:185]
	v_pk_mul_f32 v[32:33], v[32:33], v[186:187]
	v_pk_mul_f32 v[26:27], v[26:27], v[188:189]
	v_pk_mul_f32 v[28:29], v[28:29], v[190:191]
	v_cvt_pk_bf16_f32 v162, v30, v31
	v_cvt_pk_bf16_f32 v163, v32, v33
	v_cvt_pk_bf16_f32 v164, v26, v27
	v_cvt_pk_bf16_f32 v165, v28, v29
	global_store_dwordx4 v[208:209], v[162:165], off
	v_pk_mul_f32 v[22:23], v[22:23], v[142:143] op_sel_hi:[1,0]
	v_pk_mul_f32 v[24:25], v[24:25], v[142:143] op_sel_hi:[1,0]
	v_pk_mul_f32 v[18:19], v[18:19], v[142:143] op_sel_hi:[1,0]
	v_pk_mul_f32 v[20:21], v[20:21], v[142:143] op_sel_hi:[1,0]
	v_pk_mul_f32 v[184:185], v[22:23], s[28:29] op_sel_hi:[1,0]
	v_pk_mul_f32 v[186:187], v[24:25], s[28:29] op_sel_hi:[1,0]
	v_pk_mul_f32 v[188:189], v[18:19], s[28:29] op_sel_hi:[1,0]
	v_pk_mul_f32 v[190:191], v[20:21], s[28:29] op_sel_hi:[1,0]
	v_pk_mul_f32 v[184:185], v[22:23], v[184:185]
	v_pk_mul_f32 v[186:187], v[24:25], v[186:187]
	v_pk_mul_f32 v[188:189], v[18:19], v[188:189]
	v_pk_mul_f32 v[190:191], v[20:21], v[190:191]
	v_pk_fma_f32 v[184:185], v[22:23], v[184:185], v[22:23]
	v_pk_fma_f32 v[186:187], v[24:25], v[186:187], v[24:25]
	v_pk_fma_f32 v[188:189], v[18:19], v[188:189], v[18:19]
	v_pk_fma_f32 v[190:191], v[20:21], v[190:191], v[20:21]
	v_pk_mul_f32 v[184:185], v[184:185], s[8:9] op_sel_hi:[1,0]
	v_pk_mul_f32 v[186:187], v[186:187], s[8:9] op_sel_hi:[1,0]
	v_pk_mul_f32 v[188:189], v[188:189], s[8:9] op_sel_hi:[1,0]
	v_pk_mul_f32 v[190:191], v[190:191], s[8:9] op_sel_hi:[1,0]
	v_pk_mul_f32 v[184:185], v[184:185], s[26:27] op_sel_hi:[1,0]
	v_pk_mul_f32 v[186:187], v[186:187], s[26:27] op_sel_hi:[1,0]
	v_pk_mul_f32 v[188:189], v[188:189], s[26:27] op_sel_hi:[1,0]
	v_pk_mul_f32 v[190:191], v[190:191], s[26:27] op_sel_hi:[1,0]
	v_exp_f32_e32 v184, v184
	v_exp_f32_e32 v185, v185
	v_exp_f32_e32 v186, v186
	v_exp_f32_e32 v187, v187
	v_exp_f32_e32 v188, v188
	v_exp_f32_e32 v189, v189
	v_exp_f32_e32 v190, v190
	v_exp_f32_e32 v191, v191
	v_add_f32_e32 v184, 1.0, v184
	v_add_f32_e32 v185, 1.0, v185
	v_add_f32_e32 v186, 1.0, v186
	v_add_f32_e32 v187, 1.0, v187
	v_add_f32_e32 v188, 1.0, v188
	v_add_f32_e32 v189, 1.0, v189
	v_add_f32_e32 v190, 1.0, v190
	v_add_f32_e32 v191, 1.0, v191
	v_rcp_f32_e32 v184, v184
	v_rcp_f32_e32 v185, v185
	v_rcp_f32_e32 v186, v186
	v_rcp_f32_e32 v187, v187
	v_rcp_f32_e32 v188, v188
	v_rcp_f32_e32 v189, v189
	v_rcp_f32_e32 v190, v190
	v_rcp_f32_e32 v191, v191
	s_nop 0
	v_pk_mul_f32 v[22:23], v[22:23], v[184:185]
	v_pk_mul_f32 v[24:25], v[24:25], v[186:187]
	v_pk_mul_f32 v[18:19], v[18:19], v[188:189]
	v_pk_mul_f32 v[20:21], v[20:21], v[190:191]
	v_cvt_pk_bf16_f32 v148, v22, v23
	v_cvt_pk_bf16_f32 v149, v24, v25
	v_cvt_pk_bf16_f32 v150, v18, v19
	v_cvt_pk_bf16_f32 v151, v20, v21
	global_store_dwordx4 v[208:209], v[148:151], off offset:256
	v_mad_i64_i32 v[208:209], vcc, s41, v183, 0
	v_lshl_add_u64 v[208:209], v[208:209], 1, v[214:215]
	v_pk_mul_f32 v[14:15], v[14:15], v[144:145] op_sel_hi:[1,0]
	v_pk_mul_f32 v[16:17], v[16:17], v[144:145] op_sel_hi:[1,0]
	v_pk_mul_f32 v[10:11], v[10:11], v[144:145] op_sel_hi:[1,0]
	v_pk_mul_f32 v[12:13], v[12:13], v[144:145] op_sel_hi:[1,0]
	v_pk_mul_f32 v[184:185], v[14:15], s[28:29] op_sel_hi:[1,0]
	v_pk_mul_f32 v[186:187], v[16:17], s[28:29] op_sel_hi:[1,0]
	v_pk_mul_f32 v[188:189], v[10:11], s[28:29] op_sel_hi:[1,0]
	v_pk_mul_f32 v[190:191], v[12:13], s[28:29] op_sel_hi:[1,0]
	v_pk_mul_f32 v[184:185], v[14:15], v[184:185]
	v_pk_mul_f32 v[186:187], v[16:17], v[186:187]
	v_pk_mul_f32 v[188:189], v[10:11], v[188:189]
	v_pk_mul_f32 v[190:191], v[12:13], v[190:191]
	v_pk_fma_f32 v[184:185], v[14:15], v[184:185], v[14:15]
	v_pk_fma_f32 v[186:187], v[16:17], v[186:187], v[16:17]
	v_pk_fma_f32 v[188:189], v[10:11], v[188:189], v[10:11]
	v_pk_fma_f32 v[190:191], v[12:13], v[190:191], v[12:13]
	v_pk_mul_f32 v[184:185], v[184:185], s[8:9] op_sel_hi:[1,0]
	v_pk_mul_f32 v[186:187], v[186:187], s[8:9] op_sel_hi:[1,0]
	v_pk_mul_f32 v[188:189], v[188:189], s[8:9] op_sel_hi:[1,0]
	v_pk_mul_f32 v[190:191], v[190:191], s[8:9] op_sel_hi:[1,0]
	v_pk_mul_f32 v[184:185], v[184:185], s[26:27] op_sel_hi:[1,0]
	v_pk_mul_f32 v[186:187], v[186:187], s[26:27] op_sel_hi:[1,0]
	v_pk_mul_f32 v[188:189], v[188:189], s[26:27] op_sel_hi:[1,0]
	v_pk_mul_f32 v[190:191], v[190:191], s[26:27] op_sel_hi:[1,0]
	v_exp_f32_e32 v184, v184
	v_exp_f32_e32 v185, v185
	v_exp_f32_e32 v186, v186
	v_exp_f32_e32 v187, v187
	v_exp_f32_e32 v188, v188
	v_exp_f32_e32 v189, v189
	v_exp_f32_e32 v190, v190
	v_exp_f32_e32 v191, v191
	v_add_f32_e32 v184, 1.0, v184
	v_add_f32_e32 v185, 1.0, v185
	v_add_f32_e32 v186, 1.0, v186
	v_add_f32_e32 v187, 1.0, v187
	v_add_f32_e32 v188, 1.0, v188
	v_add_f32_e32 v189, 1.0, v189
	v_add_f32_e32 v190, 1.0, v190
	v_add_f32_e32 v191, 1.0, v191
	v_rcp_f32_e32 v184, v184
	v_rcp_f32_e32 v185, v185
	v_rcp_f32_e32 v186, v186
	v_rcp_f32_e32 v187, v187
	v_rcp_f32_e32 v188, v188
	v_rcp_f32_e32 v189, v189
	v_rcp_f32_e32 v190, v190
	v_rcp_f32_e32 v191, v191
	s_nop 0
	v_pk_mul_f32 v[14:15], v[14:15], v[184:185]
	v_pk_mul_f32 v[16:17], v[16:17], v[186:187]
	v_pk_mul_f32 v[10:11], v[10:11], v[188:189]
	v_pk_mul_f32 v[12:13], v[12:13], v[190:191]
	v_cvt_pk_bf16_f32 v162, v14, v15
	v_cvt_pk_bf16_f32 v163, v16, v17
	v_cvt_pk_bf16_f32 v164, v10, v11
	v_cvt_pk_bf16_f32 v165, v12, v13
	global_store_dwordx4 v[208:209], v[162:165], off
	v_pk_mul_f32 v[6:7], v[6:7], v[144:145] op_sel_hi:[1,0]
	v_pk_mul_f32 v[8:9], v[8:9], v[144:145] op_sel_hi:[1,0]
	v_pk_mul_f32 v[2:3], v[2:3], v[144:145] op_sel_hi:[1,0]
	v_pk_mul_f32 v[4:5], v[4:5], v[144:145] op_sel_hi:[1,0]
	v_pk_mul_f32 v[184:185], v[6:7], s[28:29] op_sel_hi:[1,0]
	v_pk_mul_f32 v[186:187], v[8:9], s[28:29] op_sel_hi:[1,0]
	v_pk_mul_f32 v[188:189], v[2:3], s[28:29] op_sel_hi:[1,0]
	v_pk_mul_f32 v[190:191], v[4:5], s[28:29] op_sel_hi:[1,0]
	v_pk_mul_f32 v[184:185], v[6:7], v[184:185]
	v_pk_mul_f32 v[186:187], v[8:9], v[186:187]
	v_pk_mul_f32 v[188:189], v[2:3], v[188:189]
	v_pk_mul_f32 v[190:191], v[4:5], v[190:191]
	v_pk_fma_f32 v[184:185], v[6:7], v[184:185], v[6:7]
	v_pk_fma_f32 v[186:187], v[8:9], v[186:187], v[8:9]
	v_pk_fma_f32 v[188:189], v[2:3], v[188:189], v[2:3]
	v_pk_fma_f32 v[190:191], v[4:5], v[190:191], v[4:5]
	v_pk_mul_f32 v[184:185], v[184:185], s[8:9] op_sel_hi:[1,0]
	v_pk_mul_f32 v[186:187], v[186:187], s[8:9] op_sel_hi:[1,0]
	v_pk_mul_f32 v[188:189], v[188:189], s[8:9] op_sel_hi:[1,0]
	v_pk_mul_f32 v[190:191], v[190:191], s[8:9] op_sel_hi:[1,0]
	v_pk_mul_f32 v[184:185], v[184:185], s[26:27] op_sel_hi:[1,0]
	v_pk_mul_f32 v[186:187], v[186:187], s[26:27] op_sel_hi:[1,0]
	v_pk_mul_f32 v[188:189], v[188:189], s[26:27] op_sel_hi:[1,0]
	v_pk_mul_f32 v[190:191], v[190:191], s[26:27] op_sel_hi:[1,0]
	v_exp_f32_e32 v184, v184
	v_exp_f32_e32 v185, v185
	v_exp_f32_e32 v186, v186
	v_exp_f32_e32 v187, v187
	v_exp_f32_e32 v188, v188
	v_exp_f32_e32 v189, v189
	v_exp_f32_e32 v190, v190
	v_exp_f32_e32 v191, v191
	v_add_f32_e32 v184, 1.0, v184
	v_add_f32_e32 v185, 1.0, v185
	v_add_f32_e32 v186, 1.0, v186
	v_add_f32_e32 v187, 1.0, v187
	v_add_f32_e32 v188, 1.0, v188
	v_add_f32_e32 v189, 1.0, v189
	v_add_f32_e32 v190, 1.0, v190
	v_add_f32_e32 v191, 1.0, v191
	v_rcp_f32_e32 v184, v184
	v_rcp_f32_e32 v185, v185
	v_rcp_f32_e32 v186, v186
	v_rcp_f32_e32 v187, v187
	v_rcp_f32_e32 v188, v188
	v_rcp_f32_e32 v189, v189
	v_rcp_f32_e32 v190, v190
	v_rcp_f32_e32 v191, v191
	s_nop 0
	v_pk_mul_f32 v[6:7], v[6:7], v[184:185]
	v_pk_mul_f32 v[8:9], v[8:9], v[186:187]
	v_pk_mul_f32 v[2:3], v[2:3], v[188:189]
	v_pk_mul_f32 v[4:5], v[4:5], v[190:191]
	v_cvt_pk_bf16_f32 v148, v6, v7
	v_cvt_pk_bf16_f32 v149, v8, v9
	v_cvt_pk_bf16_f32 v150, v2, v3
	v_cvt_pk_bf16_f32 v151, v4, v5
	global_store_dwordx4 v[208:209], v[148:151], off offset:256
.Lpj_fin:
	s_andn2_b64 vcc, exec, s[4:5]
	s_mov_b64 s[4:5], -1
	s_cbranch_vccnz .LBB0_801
	s_branch .Lpj_1085
